# v60 + softmax: exps in place with row-sum pk_add, bf16 packing and P lane swaps interleaved between the exps
# baseline (speedup 1.0000x reference)
; __device__ __forceinline__ bool softmax_pp(f32x16& p0, f32x16& p1, float& m_reg, float& l_reg, f32x16& negm, float& alpha, float& m_run, float dq, float nslope,
;                                            bf16x8& pa0, bf16x8& pa1, bf16x8& pa2, bf16x8& pa3) {
;     ...
;   for (int r = 0; r < 16; ++r) { p0[r] = __builtin_amdgcn_exp2f(p0[r]); p1[r] = __builtin_amdgcn_exp2f(p1[r]); }
;   float ps = 0;
; #pragma unroll
;   for (int r = 0; r < 16; ++r) ps += p0[r];
; #pragma unroll
;   for (int r = 0; r < 16; ++r) ps += p1[r];
;   { auto rr = __builtin_amdgcn_permlane32_swap(__float_as_uint(ps), __float_as_uint(ps), false, false);
;     ps = __uint_as_float(rr[0]) + __uint_as_float(rr[1]); }
;   l_reg = l_reg * alpha + ps;
;     ...
;   PK4(p0, 0, pa0); PK4(p0, 8, pa1); PK4(p1, 0, pa2); PK4(p1, 8, pa3);
.LBB0_369:
	v_max_f32_e32 v172, v172, v15
	v_exp_f32_e32 v98, v98
	v_exp_f32_e32 v99, v99
	v_exp_f32_e32 v100, v100
	v_exp_f32_e32 v101, v101
	v_cvt_pk_bf16_f32 v2, v98, v99
	v_exp_f32_e32 v102, v102
	v_exp_f32_e32 v103, v103
	v_pk_add_f32 v[14:15], v[98:99], v[100:101]
	v_cvt_pk_bf16_f32 v3, v100, v101
	v_exp_f32_e32 v104, v104
	v_exp_f32_e32 v105, v105
	v_pk_add_f32 v[14:15], v[14:15], v[102:103]
	v_cvt_pk_bf16_f32 v4, v102, v103
	v_exp_f32_e32 v106, v106
	v_exp_f32_e32 v107, v107
	v_pk_add_f32 v[14:15], v[14:15], v[104:105]
	v_cvt_pk_bf16_f32 v5, v104, v105
	v_permlane32_swap_b32_e32 v2, v4
	v_exp_f32_e32 v108, v108
	v_exp_f32_e32 v109, v109
	v_pk_add_f32 v[14:15], v[14:15], v[106:107]
	v_cvt_pk_bf16_f32 v6, v106, v107
	v_permlane32_swap_b32_e32 v3, v5
	v_exp_f32_e32 v110, v110
	v_exp_f32_e32 v111, v111
	v_pk_add_f32 v[14:15], v[14:15], v[108:109]
	v_cvt_pk_bf16_f32 v7, v108, v109
	v_exp_f32_e32 v112, v112
	v_exp_f32_e32 v113, v113
	v_pk_add_f32 v[14:15], v[14:15], v[110:111]
	v_cvt_pk_bf16_f32 v8, v110, v111
	v_exp_f32_e32 v114, v114
	v_exp_f32_e32 v115, v115
	v_pk_add_f32 v[14:15], v[14:15], v[112:113]
	v_cvt_pk_bf16_f32 v9, v112, v113
	v_permlane32_swap_b32_e32 v6, v8
	v_exp_f32_e32 v116, v116
	v_exp_f32_e32 v117, v117
	v_pk_add_f32 v[14:15], v[14:15], v[114:115]
	v_cvt_pk_bf16_f32 v10, v114, v115
	v_permlane32_swap_b32_e32 v7, v9
	v_exp_f32_e32 v118, v118
	v_exp_f32_e32 v119, v119
	v_pk_add_f32 v[14:15], v[14:15], v[116:117]
	v_cvt_pk_bf16_f32 v11, v116, v117
	v_exp_f32_e32 v120, v120
	v_exp_f32_e32 v121, v121
	v_pk_add_f32 v[14:15], v[14:15], v[118:119]
	v_cvt_pk_bf16_f32 v12, v118, v119
	v_exp_f32_e32 v122, v122
	v_exp_f32_e32 v123, v123
	v_pk_add_f32 v[14:15], v[14:15], v[120:121]
	v_cvt_pk_bf16_f32 v13, v120, v121
	v_permlane32_swap_b32_e32 v10, v12
	v_exp_f32_e32 v124, v124
	v_exp_f32_e32 v125, v125
	v_pk_add_f32 v[14:15], v[14:15], v[122:123]
	v_cvt_pk_bf16_f32 v162, v122, v123
	v_permlane32_swap_b32_e32 v11, v13
	v_exp_f32_e32 v126, v126
	v_exp_f32_e32 v127, v127
	v_pk_add_f32 v[14:15], v[14:15], v[124:125]
	v_cvt_pk_bf16_f32 v163, v124, v125
	v_exp_f32_e32 v128, v128
	v_exp_f32_e32 v129, v129
	v_pk_add_f32 v[14:15], v[14:15], v[126:127]
	v_cvt_pk_bf16_f32 v164, v126, v127
	v_pk_add_f32 v[14:15], v[14:15], v[128:129]
	v_cvt_pk_bf16_f32 v165, v128, v129
	v_add_f32_e32 v14, v14, v15
	v_permlane32_swap_b32_e32 v162, v164
	v_mov_b32_e32 v15, v14
	v_permlane32_swap_b32_e32 v163, v165
	s_nop 0
	v_permlane32_swap_b32_e32 v14, v15
	v_add_f32_e32 v14, v14, v15
	v_fma_f32 v80, v80, v0, v14
	s_branch .LBB0_371

; __device__ __forceinline__ bool softmax_pp(f32x16& p0, f32x16& p1, float& m_reg, float& l_reg, f32x16& negm, float& alpha, float& m_run, float dq, float nslope,
;                                            bf16x8& pa0, bf16x8& pa1, bf16x8& pa2, bf16x8& pa3) {
;     ...
;   for (int r = 0; r < 16; ++r) { p0[r] = __builtin_amdgcn_exp2f(p0[r]); p1[r] = __builtin_amdgcn_exp2f(p1[r]); }
;   float ps = 0;
; #pragma unroll
;   for (int r = 0; r < 16; ++r) ps += p0[r];
; #pragma unroll
;   for (int r = 0; r < 16; ++r) ps += p1[r];
;   { auto rr = __builtin_amdgcn_permlane32_swap(__float_as_uint(ps), __float_as_uint(ps), false, false);
;     ps = __uint_as_float(rr[0]) + __uint_as_float(rr[1]); }
;   l_reg = l_reg * alpha + ps;
;     ...
;   PK4(p0, 0, pa0); PK4(p0, 8, pa1); PK4(p1, 0, pa2); PK4(p1, 8, pa3);
.LBB0_384:
	v_max_f32_e32 v172, v172, v15
	v_exp_f32_e32 v98, v98
	v_exp_f32_e32 v99, v99
	v_exp_f32_e32 v100, v100
	v_exp_f32_e32 v101, v101
	v_cvt_pk_bf16_f32 v2, v98, v99
	v_exp_f32_e32 v102, v102
	v_exp_f32_e32 v103, v103
	v_pk_add_f32 v[14:15], v[98:99], v[100:101]
	v_cvt_pk_bf16_f32 v3, v100, v101
	v_exp_f32_e32 v104, v104
	v_exp_f32_e32 v105, v105
	v_pk_add_f32 v[14:15], v[14:15], v[102:103]
	v_cvt_pk_bf16_f32 v4, v102, v103
	v_exp_f32_e32 v106, v106
	v_exp_f32_e32 v107, v107
	v_pk_add_f32 v[14:15], v[14:15], v[104:105]
	v_cvt_pk_bf16_f32 v5, v104, v105
	v_permlane32_swap_b32_e32 v2, v4
	v_exp_f32_e32 v108, v108
	v_exp_f32_e32 v109, v109
	v_pk_add_f32 v[14:15], v[14:15], v[106:107]
	v_cvt_pk_bf16_f32 v6, v106, v107
	v_permlane32_swap_b32_e32 v3, v5
	v_exp_f32_e32 v110, v110
	v_exp_f32_e32 v111, v111
	v_pk_add_f32 v[14:15], v[14:15], v[108:109]
	v_cvt_pk_bf16_f32 v7, v108, v109
	v_exp_f32_e32 v112, v112
	v_exp_f32_e32 v113, v113
	v_pk_add_f32 v[14:15], v[14:15], v[110:111]
	v_cvt_pk_bf16_f32 v8, v110, v111
	v_exp_f32_e32 v114, v114
	v_exp_f32_e32 v115, v115
	v_pk_add_f32 v[14:15], v[14:15], v[112:113]
	v_cvt_pk_bf16_f32 v9, v112, v113
	v_permlane32_swap_b32_e32 v6, v8
	v_exp_f32_e32 v116, v116
	v_exp_f32_e32 v117, v117
	v_pk_add_f32 v[14:15], v[14:15], v[114:115]
	v_cvt_pk_bf16_f32 v10, v114, v115
	v_permlane32_swap_b32_e32 v7, v9
	v_exp_f32_e32 v118, v118
	v_exp_f32_e32 v119, v119
	v_pk_add_f32 v[14:15], v[14:15], v[116:117]
	v_cvt_pk_bf16_f32 v11, v116, v117
	v_exp_f32_e32 v120, v120
	v_exp_f32_e32 v121, v121
	v_pk_add_f32 v[14:15], v[14:15], v[118:119]
	v_cvt_pk_bf16_f32 v12, v118, v119
	v_exp_f32_e32 v122, v122
	v_exp_f32_e32 v123, v123
	v_pk_add_f32 v[14:15], v[14:15], v[120:121]
	v_cvt_pk_bf16_f32 v13, v120, v121
	v_permlane32_swap_b32_e32 v10, v12
	v_exp_f32_e32 v124, v124
	v_exp_f32_e32 v125, v125
	v_pk_add_f32 v[14:15], v[14:15], v[122:123]
	v_cvt_pk_bf16_f32 v162, v122, v123
	v_permlane32_swap_b32_e32 v11, v13
	v_exp_f32_e32 v126, v126
	v_exp_f32_e32 v127, v127
	v_pk_add_f32 v[14:15], v[14:15], v[124:125]
	v_cvt_pk_bf16_f32 v163, v124, v125
	v_exp_f32_e32 v128, v128
	v_exp_f32_e32 v129, v129
	v_pk_add_f32 v[14:15], v[14:15], v[126:127]
	v_cvt_pk_bf16_f32 v164, v126, v127
	v_pk_add_f32 v[14:15], v[14:15], v[128:129]
	v_cvt_pk_bf16_f32 v165, v128, v129
	v_add_f32_e32 v14, v14, v15
	v_permlane32_swap_b32_e32 v162, v164
	v_mov_b32_e32 v15, v14
	v_permlane32_swap_b32_e32 v163, v165
	s_nop 0
	v_permlane32_swap_b32_e32 v14, v15
	v_add_f32_e32 v14, v14, v15
	v_fma_f32 v80, v80, v0, v14
